# RMSNorm rows: weight/scale/shift quads loaded once per item, DPP/permlane row sums
# speedup vs baseline: 1.0593x; 1.0084x over previous
; DI int otid() { int t = (int)__builtin_amdgcn_workitem_id_x(); asm volatile("" : "+v"(t)); return t; }
; DI void norm_item(const float* xin, const float* nw, const float* sh, const float* sc, bf16_t* hb, int item) {
;   const int lane = otid() & 63, wid = otid() >> 6;
;   for (int rr = 0; rr < 4; ++rr) {
;     const int t = item * 16 + wid * 4 + rr;
;     const float* xr = xin + (size_t)t * 1024;
;     f32x4 v[4]; float ss = 0.f;
; #pragma unroll
;     for (int i = 0; i < 4; ++i) { v[i] = *(const f32x4*)(xr + i * 256 + lane * 4); ss += v[i][0] * v[i][0] + v[i][1] * v[i][1] + v[i][2] * v[i][2] + v[i][3] * v[i][3]; }
;     ss = wave_sum(ss);
;     const float rstd = rsqrtf(ss * (1.f / 1024.f) + EPS);
; #pragma unroll
;     for (int i = 0; i < 4; ++i) {
;       const int c = i * 256 + lane * 4;
;       f32x4 w = *(const f32x4*)(nw + c), s1 = *(const f32x4*)(sc + c), s0 = *(const f32x4*)(sh + c);
.LBB0_115:
	v_mov_b32_e32 v0, v201
	v_mov_b32_e32 v2, v201
	v_xor_b32_e32 v3, 32, v227
	v_ashrrev_i32_e32 v2, 4, v2
	v_and_b32_e32 v4, -4, v2
	v_and_b32_e32 v2, 64, v227
	v_add_u32_e32 v2, 64, v2
	v_cmp_lt_i32_e32 vcc, v3, v2
	v_lshlrev_b32_e32 v0, 2, v0
	v_and_b32_e32 v5, 0xfc, v0
	v_cndmask_b32_e32 v3, v227, v3, vcc
	v_lshlrev_b32_e32 v42, 2, v3
	v_xor_b32_e32 v3, 16, v227
	v_cmp_lt_i32_e32 vcc, v3, v2
	v_lshlrev_b32_e32 v0, 2, v5
	v_lshl_add_u64 v[18:19], s[0:1], 0, v[0:1]
	v_cndmask_b32_e32 v3, v227, v3, vcc
	v_lshlrev_b32_e32 v43, 2, v3
	v_xor_b32_e32 v3, 8, v227
	v_cmp_lt_i32_e32 vcc, v3, v2
	v_lshl_add_u64 v[20:21], s[2:3], 0, v[0:1]
	v_lshl_add_u64 v[22:23], s[22:23], 0, v[0:1]
	v_cndmask_b32_e32 v3, v227, v3, vcc
	v_lshlrev_b32_e32 v44, 2, v3
	v_xor_b32_e32 v3, 4, v227
	v_cmp_lt_i32_e32 vcc, v3, v2
	v_lshl_add_u64 v[24:25], s[20:21], 0, v[0:1]
	s_mov_b32 s7, 0
	v_cndmask_b32_e32 v3, v227, v3, vcc
	v_lshlrev_b32_e32 v45, 2, v3
	v_xor_b32_e32 v3, 2, v227
	v_cmp_lt_i32_e32 vcc, v3, v2
	v_add_u32_e32 v48, s5, v4
	s_nop 0
	v_cndmask_b32_e32 v3, v227, v3, vcc
	v_lshlrev_b32_e32 v46, 2, v3
	v_xor_b32_e32 v3, 1, v227
	v_cmp_lt_i32_e32 vcc, v3, v2
	s_nop 1
	v_cndmask_b32_e32 v2, v227, v3, vcc
	v_lshlrev_b32_e32 v47, 2, v2
	v_or_b32_e32 v2, 0x400, v0
	v_mov_b32_e32 v3, v1
	v_lshl_add_u64 v[26:27], s[22:23], 0, v[2:3]
	v_lshl_add_u64 v[28:29], s[20:21], 0, v[2:3]
	v_or_b32_e32 v2, 0x800, v0
	v_or_b32_e32 v0, 0xc00, v0
	v_lshl_add_u64 v[34:35], s[22:23], 0, v[0:1]
	v_lshl_add_u64 v[36:37], s[20:21], 0, v[0:1]
	v_lshlrev_b32_e32 v0, 1, v5
	v_lshl_add_u64 v[30:31], s[22:23], 0, v[2:3]
	v_lshl_add_u64 v[32:33], s[20:21], 0, v[2:3]
	v_lshl_add_u64 v[38:39], s[24:25], 0, v[0:1]
	global_load_dwordx4 v[70:73], v[20:21], off
	global_load_dwordx4 v[74:77], v[22:23], off
	global_load_dwordx4 v[78:81], v[24:25], off
	global_load_dwordx4 v[82:85], v[20:21], off offset:1024
	global_load_dwordx4 v[86:89], v[26:27], off
	global_load_dwordx4 v[90:93], v[28:29], off
	global_load_dwordx4 v[94:97], v[20:21], off offset:2048
	global_load_dwordx4 v[98:101], v[30:31], off
	global_load_dwordx4 v[102:105], v[32:33], off
	global_load_dwordx4 v[106:109], v[20:21], off offset:3072
	global_load_dwordx4 v[110:113], v[34:35], off
	global_load_dwordx4 v[114:117], v[36:37], off
	s_waitcnt vmcnt(0)
; DI unsigned pk2(float lo, float hi) { f32x2_t v; v[0] = lo; v[1] = hi; bf16x2_t b = __builtin_convertvector(v, bf16x2_t); return __builtin_bit_cast(unsigned, b); }
; DI float wave_sum(float v) {
; #pragma unroll
;   for (int o = 32; o >= 1; o >>= 1) v += __shfl_xor(v, o);
;   return v;
; }
; DI void norm_item(const float* xin, const float* nw, const float* sh, const float* sc, bf16_t* hb, int item) {
;     ...
;   for (int rr = 0; rr < 4; ++rr) {
;     const int t = item * 16 + wid * 4 + rr;
;     const float* xr = xin + (size_t)t * 1024;
;     f32x4 v[4]; float ss = 0.f;
; #pragma unroll
;     for (int i = 0; i < 4; ++i) { v[i] = *(const f32x4*)(xr + i * 256 + lane * 4); ss += v[i][0] * v[i][0] + v[i][1] * v[i][1] + v[i][2] * v[i][2] + v[i][3] * v[i][3]; }
;     ss = wave_sum(ss);
;     const float rstd = rsqrtf(ss * (1.f / 1024.f) + EPS);
; #pragma unroll
;     for (int i = 0; i < 4; ++i) {
;       const int c = i * 256 + lane * 4;
;       f32x4 w = *(const f32x4*)(nw + c), s1 = *(const f32x4*)(sc + c), s0 = *(const f32x4*)(sh + c);
;       float y0 = v[i][0] * rstd * w[0] * (1.f + s1[0]) + s0[0], y1 = v[i][1] * rstd * w[1] * (1.f + s1[1]) + s0[1];
;       float y2 = v[i][2] * rstd * w[2] * (1.f + s1[2]) + s0[2], y3 = v[i][3] * rstd * w[3] * (1.f + s1[3]) + s0[3];
;       u32x2 o; o.x = pk2(y0, y1); o.y = pk2(y2, y3);
;       *(u32x2*)(hb + (size_t)t * 1024 + c) = o;
;     }
.LBB0_116:
	v_add_u32_e32 v40, s7, v48
	v_ashrrev_i32_e32 v41, 31, v40
	v_lshlrev_b64 v[2:3], 12, v[40:41]
	v_lshl_add_u64 v[2:3], v[18:19], 0, v[2:3]
	global_load_dwordx4 v[14:17], v[2:3], off
	global_load_dwordx4 v[6:9], v[2:3], off offset:1024
	s_add_i32 s7, s7, 1
	s_cmp_lg_u32 s7, 4
	s_waitcnt vmcnt(1)
	v_mov_b32_e32 v10, v15
	s_waitcnt vmcnt(0)
	v_mov_b32_e32 v11, v7
	v_mov_b32_e32 v4, v14
	v_mov_b32_e32 v5, v6
	v_pk_mul_f32 v[10:11], v[10:11], v[10:11]
	s_nop 0
	v_pk_fma_f32 v[4:5], v[4:5], v[4:5], v[10:11]
	v_mov_b32_e32 v10, v16
	v_mov_b32_e32 v11, v8
	v_pk_fma_f32 v[4:5], v[10:11], v[10:11], v[4:5]
	v_mov_b32_e32 v10, v17
	v_mov_b32_e32 v11, v9
	v_pk_fma_f32 v[50:51], v[10:11], v[10:11], v[4:5]
	global_load_dwordx4 v[10:13], v[2:3], off offset:2048
	s_nop 0
	global_load_dwordx4 v[2:5], v[2:3], off offset:3072
	v_add_f32_e32 v0, v50, v51
	s_waitcnt vmcnt(1)
	v_mov_b32_e32 v54, v11
	s_waitcnt vmcnt(0)
	v_mov_b32_e32 v55, v3
	v_mov_b32_e32 v52, v10
	v_mov_b32_e32 v53, v2
	v_pk_mul_f32 v[54:55], v[54:55], v[54:55]
	s_nop 0
	v_pk_fma_f32 v[52:53], v[52:53], v[52:53], v[54:55]
	v_mov_b32_e32 v54, v12
	v_mov_b32_e32 v55, v4
	v_pk_fma_f32 v[52:53], v[54:55], v[54:55], v[52:53]
	v_mov_b32_e32 v54, v13
	v_mov_b32_e32 v55, v5
	v_pk_fma_f32 v[52:53], v[54:55], v[54:55], v[52:53]
	s_nop 0
	v_add_f32_e32 v0, v0, v52
	v_add_f32_e32 v0, v0, v53
	v_mov_b32_e32 v50, v70
	v_mov_b32_e32 v51, v71
	v_mov_b32_e32 v52, v72
	v_mov_b32_e32 v53, v73
	v_mov_b32_e32 v54, v74
	v_mov_b32_e32 v55, v75
	v_mov_b32_e32 v56, v76
	v_mov_b32_e32 v57, v77
	v_mov_b32_e32 v58, v78
	v_mov_b32_e32 v59, v79
	v_mov_b32_e32 v60, v80
	v_mov_b32_e32 v61, v81
	s_nop 1
	v_add_f32_dpp v0, v0, v0 quad_perm:[1,0,3,2] row_mask:0xf bank_mask:0xf
	s_nop 1
	v_add_f32_dpp v0, v0, v0 quad_perm:[2,3,0,1] row_mask:0xf bank_mask:0xf
	s_nop 1
	v_add_f32_dpp v0, v0, v0 row_half_mirror row_mask:0xf bank_mask:0xf
	s_nop 1
	v_add_f32_dpp v0, v0, v0 row_mirror row_mask:0xf bank_mask:0xf
	v_mov_b32_e32 v49, v0
	s_nop 1
	v_permlane16_swap_b32_e32 v0, v49
	s_nop 1
	v_add_f32_e32 v0, v0, v49
	v_mov_b32_e32 v49, v0
	s_nop 1
	v_permlane32_swap_b32_e32 v0, v49
	s_nop 1
	v_add_f32_e32 v0, v0, v49
	v_fmamk_f32 v0, v0, 0x3a800000, v200
	v_cmp_gt_f32_e32 vcc, s58, v0
	v_mul_f32_e32 v49, 0x4b800000, v0
	s_nop 0
	v_cndmask_b32_e32 v0, v0, v49, vcc
	v_rsq_f32_e32 v0, v0
	s_nop 0
	v_mul_f32_e32 v49, 0x45800000, v0
	v_cndmask_b32_e32 v0, v0, v49, vcc
	v_pk_mul_f32 v[14:15], v[14:15], v[0:1] op_sel_hi:[1,0]
	v_pk_mul_f32 v[16:17], v[16:17], v[0:1] op_sel_hi:[1,0]
	v_pk_mul_f32 v[6:7], v[6:7], v[0:1] op_sel_hi:[1,0]
	v_pk_mul_f32 v[8:9], v[8:9], v[0:1] op_sel_hi:[1,0]
	v_pk_mul_f32 v[10:11], v[10:11], v[0:1] op_sel_hi:[1,0]
	v_pk_mul_f32 v[2:3], v[2:3], v[0:1] op_sel_hi:[1,0]
	v_pk_mul_f32 v[4:5], v[4:5], v[0:1] op_sel_hi:[1,0]
	v_pk_mul_f32 v[14:15], v[50:51], v[14:15]
	v_pk_add_f32 v[50:51], v[54:55], 1.0 op_sel_hi:[1,0]
	v_pk_mul_f32 v[16:17], v[52:53], v[16:17]
	v_pk_fma_f32 v[14:15], v[50:51], v[14:15], v[58:59]
	v_pk_add_f32 v[50:51], v[56:57], 1.0 op_sel_hi:[1,0]
	s_nop 0
	v_pk_fma_f32 v[50:51], v[50:51], v[16:17], v[60:61]
	v_cvt_pk_bf16_f32 v16, v14, v15
	v_lshlrev_b64 v[14:15], 11, v[40:41]
	v_cvt_pk_bf16_f32 v17, v50, v51
	v_lshl_add_u64 v[14:15], v[38:39], 0, v[14:15]
	global_store_dwordx2 v[14:15], v[16:17], off
	v_mov_b32_e32 v50, v82
	v_mov_b32_e32 v51, v83
	v_mov_b32_e32 v52, v84
	v_mov_b32_e32 v53, v85
	v_mov_b32_e32 v54, v86
	v_mov_b32_e32 v55, v87
	v_mov_b32_e32 v56, v88
	v_mov_b32_e32 v57, v89
	v_mov_b32_e32 v58, v90
	v_mov_b32_e32 v59, v91
	v_mov_b32_e32 v60, v92
	v_mov_b32_e32 v61, v93
	v_pk_mul_f32 v[6:7], v[50:51], v[6:7]
	v_pk_add_f32 v[16:17], v[54:55], 1.0 op_sel_hi:[1,0]
	v_pk_mul_f32 v[8:9], v[52:53], v[8:9]
	v_pk_fma_f32 v[6:7], v[16:17], v[6:7], v[58:59]
	v_pk_add_f32 v[16:17], v[56:57], 1.0 op_sel_hi:[1,0]
	v_cvt_pk_bf16_f32 v6, v6, v7
	v_pk_fma_f32 v[8:9], v[16:17], v[8:9], v[60:61]
	s_nop 0
	v_cvt_pk_bf16_f32 v7, v8, v9
	global_store_dwordx2 v[14:15], v[6:7], off offset:512
	v_mov_b32_e32 v6, v94
	v_mov_b32_e32 v7, v95
	v_mov_b32_e32 v8, v96
	v_mov_b32_e32 v9, v97
	s_nop 0
	v_mov_b32_e32 v50, v98
	v_mov_b32_e32 v51, v99
	v_mov_b32_e32 v52, v100
	v_mov_b32_e32 v53, v101
	v_mov_b32_e32 v54, v102
	v_mov_b32_e32 v55, v103
	v_mov_b32_e32 v56, v104
	v_mov_b32_e32 v57, v105
	v_pk_mul_f32 v[6:7], v[6:7], v[10:11]
	v_pk_add_f32 v[10:11], v[50:51], 1.0 op_sel_hi:[1,0]
	v_pk_fma_f32 v[6:7], v[10:11], v[6:7], v[54:55]
	v_pk_mul_f32 v[10:11], v[12:13], v[0:1] op_sel_hi:[1,0]
	v_cvt_pk_bf16_f32 v6, v6, v7
	v_pk_mul_f32 v[8:9], v[8:9], v[10:11]
	v_pk_add_f32 v[10:11], v[52:53], 1.0 op_sel_hi:[1,0]
	s_nop 0
	v_pk_fma_f32 v[8:9], v[10:11], v[8:9], v[56:57]
	s_nop 0
	v_cvt_pk_bf16_f32 v7, v8, v9
	global_store_dwordx2 v[14:15], v[6:7], off offset:1024
	v_mov_b32_e32 v6, v106
	v_mov_b32_e32 v7, v107
	v_mov_b32_e32 v8, v108
	v_mov_b32_e32 v9, v109
	s_nop 0
	v_mov_b32_e32 v10, v110
	v_mov_b32_e32 v11, v111
	v_mov_b32_e32 v12, v112
	v_mov_b32_e32 v13, v113
	v_mov_b32_e32 v50, v114
	v_mov_b32_e32 v51, v115
	v_mov_b32_e32 v52, v116
	v_mov_b32_e32 v53, v117
	v_pk_mul_f32 v[2:3], v[2:3], v[6:7]
	v_pk_add_f32 v[6:7], v[10:11], 1.0 op_sel_hi:[1,0]
	v_pk_mul_f32 v[4:5], v[4:5], v[8:9]
	v_pk_fma_f32 v[2:3], v[2:3], v[6:7], v[50:51]
	v_pk_add_f32 v[6:7], v[12:13], 1.0 op_sel_hi:[1,0]
	v_cvt_pk_bf16_f32 v2, v2, v3
	v_pk_fma_f32 v[4:5], v[4:5], v[6:7], v[52:53]
	s_nop 0
	v_cvt_pk_bf16_f32 v3, v4, v5
	global_store_dwordx2 v[14:15], v[2:3], off offset:1536
	s_cbranch_scc1 .LBB0_116
	s_add_i32 s6, s6, s76
	s_add_i32 s5, s5, s4
	s_cmpk_gt_i32 s6, 0x3ff
	s_cbranch_scc0 .LBB0_115

; DI int otid() { int t = (int)__builtin_amdgcn_workitem_id_x(); asm volatile("" : "+v"(t)); return t; }
; DI void norm_item(const float* xin, const float* nw, const float* sh, const float* sc, bf16_t* hb, int item) {
;   const int lane = otid() & 63, wid = otid() >> 6;
;   for (int rr = 0; rr < 4; ++rr) {
;     const int t = item * 16 + wid * 4 + rr;
;     const float* xr = xin + (size_t)t * 1024;
;     f32x4 v[4]; float ss = 0.f;
; #pragma unroll
;     for (int i = 0; i < 4; ++i) { v[i] = *(const f32x4*)(xr + i * 256 + lane * 4); ss += v[i][0] * v[i][0] + v[i][1] * v[i][1] + v[i][2] * v[i][2] + v[i][3] * v[i][3]; }
;     ss = wave_sum(ss);
;     const float rstd = rsqrtf(ss * (1.f / 1024.f) + EPS);
; #pragma unroll
;     for (int i = 0; i < 4; ++i) {
;       const int c = i * 256 + lane * 4;
;       f32x4 w = *(const f32x4*)(nw + c), s1 = *(const f32x4*)(sc + c), s0 = *(const f32x4*)(sh + c);
.LBB0_990:
	v_mov_b32_e32 v0, v201
	v_mov_b32_e32 v2, v201
	v_xor_b32_e32 v3, 32, v227
	v_ashrrev_i32_e32 v2, 4, v2
	v_and_b32_e32 v4, -4, v2
	v_and_b32_e32 v2, 64, v227
	v_add_u32_e32 v2, 64, v2
	v_cmp_lt_i32_e32 vcc, v3, v2
	v_lshlrev_b32_e32 v0, 2, v0
	v_and_b32_e32 v5, 0xfc, v0
	v_cndmask_b32_e32 v3, v227, v3, vcc
	v_lshlrev_b32_e32 v36, 2, v3
	v_xor_b32_e32 v3, 16, v227
	v_cmp_lt_i32_e32 vcc, v3, v2
	v_lshlrev_b32_e32 v0, 2, v5
	v_readlane_b32 s10, v254, 48
	v_cndmask_b32_e32 v3, v227, v3, vcc
	v_lshlrev_b32_e32 v37, 2, v3
	v_xor_b32_e32 v3, 8, v227
	v_cmp_lt_i32_e32 vcc, v3, v2
	v_readlane_b32 s11, v254, 49
	v_lshl_add_u64 v[20:21], s[0:1], 0, v[0:1]
	v_cndmask_b32_e32 v3, v227, v3, vcc
	v_lshlrev_b32_e32 v38, 2, v3
	v_xor_b32_e32 v3, 4, v227
	v_cmp_lt_i32_e32 vcc, v3, v2
	v_lshl_add_u64 v[18:19], s[10:11], 0, v[0:1]
	v_lshl_add_u64 v[22:23], s[2:3], 0, v[0:1]
	v_cndmask_b32_e32 v3, v227, v3, vcc
	v_lshlrev_b32_e32 v39, 2, v3
	v_xor_b32_e32 v3, 2, v227
	v_cmp_lt_i32_e32 vcc, v3, v2
	v_lshl_add_u64 v[24:25], s[8:9], 0, v[0:1]
	s_mov_b32 s7, 0
	v_cndmask_b32_e32 v3, v227, v3, vcc
	v_lshlrev_b32_e32 v40, 2, v3
	v_xor_b32_e32 v3, 1, v227
	v_cmp_lt_i32_e32 vcc, v3, v2
	v_add_u32_e32 v42, s5, v4
	s_nop 0
	v_cndmask_b32_e32 v2, v227, v3, vcc
	v_lshlrev_b32_e32 v41, 2, v2
	v_or_b32_e32 v2, 0x400, v0
	v_mov_b32_e32 v3, v1
	v_lshl_add_u64 v[26:27], s[2:3], 0, v[2:3]
	v_or_b32_e32 v2, 0x800, v0
	v_or_b32_e32 v0, 0xc00, v0
	v_lshl_add_u64 v[30:31], s[2:3], 0, v[0:1]
	v_lshlrev_b32_e32 v0, 1, v5
	v_lshl_add_u64 v[28:29], s[2:3], 0, v[2:3]
	v_lshl_add_u64 v[32:33], s[20:21], 0, v[0:1]
	global_load_dwordx4 v[70:73], v[20:21], off
	global_load_dwordx4 v[74:77], v[22:23], off
	global_load_dwordx4 v[78:81], v[24:25], off
	global_load_dwordx4 v[82:85], v[20:21], off offset:1024
	global_load_dwordx4 v[86:89], v[26:27], off
	global_load_dwordx4 v[90:93], v[24:25], off offset:1024
	global_load_dwordx4 v[94:97], v[20:21], off offset:2048
	global_load_dwordx4 v[98:101], v[28:29], off
	global_load_dwordx4 v[102:105], v[24:25], off offset:2048
	global_load_dwordx4 v[106:109], v[20:21], off offset:3072
	global_load_dwordx4 v[110:113], v[30:31], off
	global_load_dwordx4 v[114:117], v[24:25], off offset:3072
	s_waitcnt vmcnt(0)
; DI unsigned pk2(float lo, float hi) { f32x2_t v; v[0] = lo; v[1] = hi; bf16x2_t b = __builtin_convertvector(v, bf16x2_t); return __builtin_bit_cast(unsigned, b); }
; DI float wave_sum(float v) {
; #pragma unroll
;   for (int o = 32; o >= 1; o >>= 1) v += __shfl_xor(v, o);
;   return v;
; }
; DI void norm_item(const float* xin, const float* nw, const float* sh, const float* sc, bf16_t* hb, int item) {
;     ...
;   for (int rr = 0; rr < 4; ++rr) {
;     const int t = item * 16 + wid * 4 + rr;
;     const float* xr = xin + (size_t)t * 1024;
;     f32x4 v[4]; float ss = 0.f;
; #pragma unroll
;     for (int i = 0; i < 4; ++i) { v[i] = *(const f32x4*)(xr + i * 256 + lane * 4); ss += v[i][0] * v[i][0] + v[i][1] * v[i][1] + v[i][2] * v[i][2] + v[i][3] * v[i][3]; }
;     ss = wave_sum(ss);
;     const float rstd = rsqrtf(ss * (1.f / 1024.f) + EPS);
; #pragma unroll
;     for (int i = 0; i < 4; ++i) {
;       const int c = i * 256 + lane * 4;
;       f32x4 w = *(const f32x4*)(nw + c), s1 = *(const f32x4*)(sc + c), s0 = *(const f32x4*)(sh + c);
;       float y0 = v[i][0] * rstd * w[0] * (1.f + s1[0]) + s0[0], y1 = v[i][1] * rstd * w[1] * (1.f + s1[1]) + s0[1];
;       float y2 = v[i][2] * rstd * w[2] * (1.f + s1[2]) + s0[2], y3 = v[i][3] * rstd * w[3] * (1.f + s1[3]) + s0[3];
;       u32x2 o; o.x = pk2(y0, y1); o.y = pk2(y2, y3);
;       *(u32x2*)(hb + (size_t)t * 1024 + c) = o;
;     }
.LBB0_991:
	v_add_u32_e32 v34, s7, v42
	v_ashrrev_i32_e32 v35, 31, v34
	v_lshlrev_b64 v[2:3], 12, v[34:35]
	v_lshl_add_u64 v[2:3], v[18:19], 0, v[2:3]
	global_load_dwordx4 v[14:17], v[2:3], off
	global_load_dwordx4 v[6:9], v[2:3], off offset:1024
	s_add_i32 s7, s7, 1
	s_cmp_lg_u32 s7, 4
	s_waitcnt vmcnt(1)
	v_mov_b32_e32 v10, v15
	s_waitcnt vmcnt(0)
	v_mov_b32_e32 v11, v7
	v_mov_b32_e32 v4, v14
	v_mov_b32_e32 v5, v6
	v_pk_mul_f32 v[10:11], v[10:11], v[10:11]
	s_nop 0
	v_pk_fma_f32 v[4:5], v[4:5], v[4:5], v[10:11]
	v_mov_b32_e32 v10, v16
	v_mov_b32_e32 v11, v8
	v_pk_fma_f32 v[4:5], v[10:11], v[10:11], v[4:5]
	v_mov_b32_e32 v10, v17
	v_mov_b32_e32 v11, v9
	v_pk_fma_f32 v[44:45], v[10:11], v[10:11], v[4:5]
	global_load_dwordx4 v[10:13], v[2:3], off offset:2048
	s_nop 0
	global_load_dwordx4 v[2:5], v[2:3], off offset:3072
	v_add_f32_e32 v0, v44, v45
	s_waitcnt vmcnt(1)
	v_mov_b32_e32 v48, v11
	s_waitcnt vmcnt(0)
	v_mov_b32_e32 v49, v3
	v_mov_b32_e32 v46, v10
	v_mov_b32_e32 v47, v2
	v_pk_mul_f32 v[48:49], v[48:49], v[48:49]
	s_nop 0
	v_pk_fma_f32 v[46:47], v[46:47], v[46:47], v[48:49]
	v_mov_b32_e32 v48, v12
	v_mov_b32_e32 v49, v4
	v_pk_fma_f32 v[46:47], v[48:49], v[48:49], v[46:47]
	v_mov_b32_e32 v48, v13
	v_mov_b32_e32 v49, v5
	v_pk_fma_f32 v[46:47], v[48:49], v[48:49], v[46:47]
	s_nop 0
	v_add_f32_e32 v0, v0, v46
	v_add_f32_e32 v0, v0, v47
	v_mov_b32_e32 v44, v70
	v_mov_b32_e32 v45, v71
	v_mov_b32_e32 v46, v72
	v_mov_b32_e32 v47, v73
	v_mov_b32_e32 v48, v74
	v_mov_b32_e32 v49, v75
	v_mov_b32_e32 v50, v76
	v_mov_b32_e32 v51, v77
	v_mov_b32_e32 v52, v78
	v_mov_b32_e32 v53, v79
	v_mov_b32_e32 v54, v80
	v_mov_b32_e32 v55, v81
	s_nop 1
	v_add_f32_dpp v0, v0, v0 quad_perm:[1,0,3,2] row_mask:0xf bank_mask:0xf
	s_nop 1
	v_add_f32_dpp v0, v0, v0 quad_perm:[2,3,0,1] row_mask:0xf bank_mask:0xf
	s_nop 1
	v_add_f32_dpp v0, v0, v0 row_half_mirror row_mask:0xf bank_mask:0xf
	s_nop 1
	v_add_f32_dpp v0, v0, v0 row_mirror row_mask:0xf bank_mask:0xf
	v_mov_b32_e32 v43, v0
	s_nop 1
	v_permlane16_swap_b32_e32 v0, v43
	s_nop 1
	v_add_f32_e32 v0, v0, v43
	v_mov_b32_e32 v43, v0
	s_nop 1
	v_permlane32_swap_b32_e32 v0, v43
	s_nop 1
	v_add_f32_e32 v0, v0, v43
	v_fmamk_f32 v0, v0, 0x3a800000, v200
	v_cmp_gt_f32_e32 vcc, s58, v0
	v_mul_f32_e32 v43, 0x4b800000, v0
	s_nop 0
	v_cndmask_b32_e32 v0, v0, v43, vcc
	v_rsq_f32_e32 v0, v0
	s_nop 0
	v_mul_f32_e32 v43, 0x45800000, v0
	v_cndmask_b32_e32 v0, v0, v43, vcc
	v_pk_mul_f32 v[14:15], v[14:15], v[0:1] op_sel_hi:[1,0]
	v_pk_mul_f32 v[16:17], v[16:17], v[0:1] op_sel_hi:[1,0]
	v_pk_mul_f32 v[6:7], v[6:7], v[0:1] op_sel_hi:[1,0]
	v_pk_mul_f32 v[8:9], v[8:9], v[0:1] op_sel_hi:[1,0]
	v_pk_mul_f32 v[10:11], v[10:11], v[0:1] op_sel_hi:[1,0]
	v_pk_mul_f32 v[2:3], v[2:3], v[0:1] op_sel_hi:[1,0]
	v_pk_mul_f32 v[4:5], v[4:5], v[0:1] op_sel_hi:[1,0]
	v_pk_mul_f32 v[14:15], v[44:45], v[14:15]
	v_pk_add_f32 v[44:45], v[48:49], 1.0 op_sel_hi:[1,0]
	v_pk_mul_f32 v[16:17], v[46:47], v[16:17]
	v_pk_fma_f32 v[14:15], v[44:45], v[14:15], v[52:53]
	v_pk_add_f32 v[44:45], v[50:51], 1.0 op_sel_hi:[1,0]
	s_nop 0
	v_pk_fma_f32 v[44:45], v[44:45], v[16:17], v[54:55]
	v_cvt_pk_bf16_f32 v16, v14, v15
	v_lshlrev_b64 v[14:15], 11, v[34:35]
	v_cvt_pk_bf16_f32 v17, v44, v45
	v_lshl_add_u64 v[14:15], v[32:33], 0, v[14:15]
	global_store_dwordx2 v[14:15], v[16:17], off
	v_mov_b32_e32 v44, v82
	v_mov_b32_e32 v45, v83
	v_mov_b32_e32 v46, v84
	v_mov_b32_e32 v47, v85
	v_mov_b32_e32 v48, v86
	v_mov_b32_e32 v49, v87
	v_mov_b32_e32 v50, v88
	v_mov_b32_e32 v51, v89
	v_mov_b32_e32 v52, v90
	v_mov_b32_e32 v53, v91
	v_mov_b32_e32 v54, v92
	v_mov_b32_e32 v55, v93
	v_pk_mul_f32 v[6:7], v[44:45], v[6:7]
	v_pk_add_f32 v[16:17], v[48:49], 1.0 op_sel_hi:[1,0]
	v_pk_mul_f32 v[8:9], v[46:47], v[8:9]
	v_pk_fma_f32 v[6:7], v[16:17], v[6:7], v[52:53]
	v_pk_add_f32 v[16:17], v[50:51], 1.0 op_sel_hi:[1,0]
	v_cvt_pk_bf16_f32 v6, v6, v7
	v_pk_fma_f32 v[8:9], v[16:17], v[8:9], v[54:55]
	s_nop 0
	v_cvt_pk_bf16_f32 v7, v8, v9
	global_store_dwordx2 v[14:15], v[6:7], off offset:512
	v_mov_b32_e32 v6, v94
	v_mov_b32_e32 v7, v95
	v_mov_b32_e32 v8, v96
	v_mov_b32_e32 v9, v97
	s_nop 0
	v_mov_b32_e32 v44, v98
	v_mov_b32_e32 v45, v99
	v_mov_b32_e32 v46, v100
	v_mov_b32_e32 v47, v101
	v_mov_b32_e32 v48, v102
	v_mov_b32_e32 v49, v103
	v_mov_b32_e32 v50, v104
	v_mov_b32_e32 v51, v105
	v_pk_mul_f32 v[6:7], v[6:7], v[10:11]
	v_pk_add_f32 v[10:11], v[44:45], 1.0 op_sel_hi:[1,0]
	v_pk_fma_f32 v[6:7], v[10:11], v[6:7], v[48:49]
	v_pk_mul_f32 v[10:11], v[12:13], v[0:1] op_sel_hi:[1,0]
	v_cvt_pk_bf16_f32 v6, v6, v7
	v_pk_mul_f32 v[8:9], v[8:9], v[10:11]
	v_pk_add_f32 v[10:11], v[46:47], 1.0 op_sel_hi:[1,0]
	s_nop 0
	v_pk_fma_f32 v[8:9], v[10:11], v[8:9], v[50:51]
	s_nop 0
	v_cvt_pk_bf16_f32 v7, v8, v9
	global_store_dwordx2 v[14:15], v[6:7], off offset:1024
	v_mov_b32_e32 v6, v106
	v_mov_b32_e32 v7, v107
	v_mov_b32_e32 v8, v108
	v_mov_b32_e32 v9, v109
	s_nop 0
	v_mov_b32_e32 v10, v110
	v_mov_b32_e32 v11, v111
	v_mov_b32_e32 v12, v112
	v_mov_b32_e32 v13, v113
	v_mov_b32_e32 v44, v114
	v_mov_b32_e32 v45, v115
	v_mov_b32_e32 v46, v116
	v_mov_b32_e32 v47, v117
	v_pk_mul_f32 v[2:3], v[2:3], v[6:7]
	v_pk_add_f32 v[6:7], v[10:11], 1.0 op_sel_hi:[1,0]
	v_pk_mul_f32 v[4:5], v[4:5], v[8:9]
	v_pk_fma_f32 v[2:3], v[2:3], v[6:7], v[44:45]
	v_pk_add_f32 v[6:7], v[12:13], 1.0 op_sel_hi:[1,0]
	v_cvt_pk_bf16_f32 v2, v2, v3
	v_pk_fma_f32 v[4:5], v[4:5], v[6:7], v[46:47]
	s_nop 0
	v_cvt_pk_bf16_f32 v3, v4, v5
	global_store_dwordx2 v[14:15], v[2:3], off offset:1536
	s_cbranch_scc1 .LBB0_991
	s_add_i32 s6, s6, s76
	s_add_i32 s5, s5, s4
	s_cmpk_gt_i32 s6, 0x3ff
	s_cbranch_scc0 .LBB0_990
	s_mov_b32 s19, s22
